# grid barrier acquire widened to system scope (buffer_inv sc0 sc1): removes rare stale-L2 reads seen in the baseline; plus GEMM v6, conv, phase0 changes
# speedup vs baseline: 1.0349x; 1.0349x over previous
.LBB0_15:
	buffer_inv sc0 sc1

.LBB0_112:
	s_or_b64 exec, exec, s[20:21]
	s_waitcnt vmcnt(0)
	buffer_inv sc0 sc1
	s_waitcnt vmcnt(0)

.LBB0_130:
	s_or_b64 exec, exec, s[8:9]
	s_mov_b64 s[8:9], exec
	v_mbcnt_lo_u32_b32 v0, s8, 0
	v_mbcnt_hi_u32_b32 v0, s9, v0
	v_cmp_eq_u32_e32 vcc, 0, v0
	s_waitcnt vmcnt(0)
	buffer_inv sc0 sc1
	s_and_saveexec_b64 s[20:21], vcc
	s_cbranch_execz .LBB0_132
	s_bcnt1_i32_b64 s4, s[8:9]
	v_mov_b32_e32 v1, s4
	v_readlane_b32 s4, v254, 17
	v_mov_b32_e32 v0, 0
	v_readlane_b32 s5, v254, 18
	s_nop 4
	global_atomic_add v0, v1, s[4:5]

.LBB0_247:
	s_or_b64 exec, exec, s[26:27]
	s_waitcnt vmcnt(0)
	buffer_inv sc0 sc1
	s_waitcnt vmcnt(0)

.LBB0_265:
	s_or_b64 exec, exec, s[24:25]
	s_mov_b64 s[24:25], exec
	v_mbcnt_lo_u32_b32 v0, s24, 0
	v_mbcnt_hi_u32_b32 v0, s25, v0
	v_cmp_eq_u32_e32 vcc, 0, v0
	s_waitcnt vmcnt(0)
	buffer_inv sc0 sc1
	s_and_saveexec_b64 s[26:27], vcc
	s_cbranch_execz .LBB0_267
	s_bcnt1_i32_b64 s6, s[24:25]
	v_readlane_b32 s24, v254, 17
	v_mov_b32_e32 v0, s6
	v_readlane_b32 s25, v254, 18
	s_nop 4
	global_atomic_add v145, v0, s[24:25]

.LBB0_305:
	s_or_b64 exec, exec, s[24:25]
	s_waitcnt vmcnt(0)
	buffer_inv sc0 sc1
	s_waitcnt vmcnt(0)

.LBB0_323:
	s_or_b64 exec, exec, s[20:21]
	s_mov_b64 s[20:21], exec
	v_mbcnt_lo_u32_b32 v0, s20, 0
	v_mbcnt_hi_u32_b32 v0, s21, v0
	v_cmp_eq_u32_e32 vcc, 0, v0
	s_waitcnt vmcnt(0)
	buffer_inv sc0 sc1
	s_and_saveexec_b64 s[24:25], vcc
	s_cbranch_execz .LBB0_325
	s_bcnt1_i32_b64 s6, s[20:21]
	v_readlane_b32 s20, v254, 17
	v_mov_b32_e32 v0, s6
	v_readlane_b32 s21, v254, 18
	s_nop 4
	global_atomic_add v145, v0, s[20:21]

.LBB0_496:
	s_or_b64 exec, exec, s[8:9]
	s_mov_b64 s[8:9], exec
	v_mbcnt_lo_u32_b32 v0, s8, 0
	v_mbcnt_hi_u32_b32 v0, s9, v0
	v_cmp_eq_u32_e32 vcc, 0, v0
	s_waitcnt vmcnt(0)
	buffer_inv sc0 sc1
	s_and_saveexec_b64 s[20:21], vcc
	s_cbranch_execz .LBB0_498
	s_bcnt1_i32_b64 s6, s[8:9]
	v_readlane_b32 s8, v254, 17
	v_mov_b32_e32 v0, s6
	v_readlane_b32 s9, v254, 18
	s_nop 4
	global_atomic_add v145, v0, s[8:9]

.LBB0_854:
	s_or_b64 exec, exec, s[8:9]
	s_mov_b64 s[8:9], exec
	v_mbcnt_lo_u32_b32 v0, s8, 0
	v_mbcnt_hi_u32_b32 v0, s9, v0
	v_cmp_eq_u32_e32 vcc, 0, v0
	s_waitcnt vmcnt(0)
	buffer_inv sc0 sc1
	s_and_saveexec_b64 s[20:21], vcc
	s_cbranch_execz .LBB0_134
	s_bcnt1_i32_b64 s6, s[8:9]
	v_readlane_b32 s8, v254, 17
	v_mov_b32_e32 v0, s6
	v_readlane_b32 s9, v254, 18
	s_nop 4
	global_atomic_add v145, v0, s[8:9]
	s_branch .LBB0_134
